# SwiGLU GEMM epilogues rewritten on packed f32 ops (same formula and association, about 40 VALU per row group instead of 70)
# speedup vs baseline: 1.0102x; 1.0102x over previous
; __device__ __forceinline__ unsigned cvt_pk_bf16(float lo, float hi) { unsigned r; asm volatile("v_cvt_pk_f16_f32 %0, %1, %2" : "=v"(r) : "v"(lo), "v"(hi)); return r; }
;     __device__ __forceinline__ void operator()(const f32x4 (&acc)[2][2][4][2], const Unit& u, int wr, int wc, int fr, int fq) const {
;         const int row0 = u.pm * BM + wr * 64 + fr, col0 = u.pn * HALF + wc * 32 + 8 * fq;
; #pragma unroll
;         for (int ai = 0; ai < 2; ++ai)
; #pragma unroll
;             for (int m = 0; m < 4; ++m) {
;                 const int row = row0 + ai * HALF + m * 16; const float sc = rs[row];
;                 const float sc2 = sc * sc, nsl = -1.4426950408889634f * sc;
;                 bf16_t* rowp = O + (size_t)row * ldc + col0;
;                 float h[8];
; #pragma unroll
;                 for (int n = 0; n < 2; ++n)
; #pragma unroll
;                     for (int e = 0; e < 4; ++e) { const float g = acc[ai][0][m][n][e], up = acc[ai][1][m][n][e];
;                         h[4 * n + e] = (g * up) * (sc2 * __builtin_amdgcn_rcpf(1.0f + __builtin_amdgcn_exp2f(g * nsl))); }
;                 u32x4 w; w.x = cvt_pk_bf16(h[0], h[1]); w.y = cvt_pk_bf16(h[2], h[3]); w.z = cvt_pk_bf16(h[4], h[5]); w.w = cvt_pk_bf16(h[6], h[7]);
;                 *(u32x4*)rowp = w;
;             }
;     }
.LBB0_169:
	v_lshl_add_u32 v146, s22, 8, v1
	v_ashrrev_i32_e32 v147, 31, v146
	v_lshl_add_u64 v[150:151], v[146:147], 2, s[8:9]
	global_load_dword v180, v[150:151], off
	global_load_dword v181, v[150:151], off offset:64
	global_load_dword v182, v[150:151], off offset:128
	global_load_dword v183, v[150:151], off offset:192
	global_load_dword v184, v[150:151], off offset:512
	global_load_dword v185, v[150:151], off offset:576
	global_load_dword v186, v[150:151], off offset:640
	global_load_dword v187, v[150:151], off offset:704
	v_lshl_or_b32 v158, s55, 7, v153
	v_lshlrev_b32_e32 v159, 1, v158
	v_mad_u32_u24 v174, v146, s54, v159
	s_lshl_b32 s98, s54, 4
	s_lshl_b32 s99, s54, 7
	v_mov_b32_e32 v192, 1.0
	v_mov_b32_e32 v193, 1.0
	v_add_u32_e32 v175, s99, v174
	s_andn2_b64 vcc, exec, s[2:3]
	s_mov_b64 s[2:3], -1
	s_waitcnt vmcnt(0)
	v_mul_f32_e32 v188, 0xbfb8aa3b, v180
	v_mul_f32_e32 v190, v180, v180
	v_pk_mul_f32 v[164:165], v[118:119], v[188:189] op_sel_hi:[1,0]
	v_pk_mul_f32 v[166:167], v[120:121], v[188:189] op_sel_hi:[1,0]
	v_pk_mul_f32 v[168:169], v[114:115], v[188:189] op_sel_hi:[1,0]
	v_pk_mul_f32 v[170:171], v[116:117], v[188:189] op_sel_hi:[1,0]
	v_exp_f32_e32 v164, v164
	v_exp_f32_e32 v165, v165
	v_exp_f32_e32 v166, v166
	v_exp_f32_e32 v167, v167
	v_exp_f32_e32 v168, v168
	v_exp_f32_e32 v169, v169
	v_exp_f32_e32 v170, v170
	v_exp_f32_e32 v171, v171
	v_pk_add_f32 v[164:165], v[164:165], v[192:193]
	v_pk_add_f32 v[166:167], v[166:167], v[192:193]
	v_pk_add_f32 v[168:169], v[168:169], v[192:193]
	v_pk_add_f32 v[170:171], v[170:171], v[192:193]
	v_rcp_f32_e32 v164, v164
	v_rcp_f32_e32 v165, v165
	v_rcp_f32_e32 v166, v166
	v_rcp_f32_e32 v167, v167
	v_rcp_f32_e32 v168, v168
	v_rcp_f32_e32 v169, v169
	v_rcp_f32_e32 v170, v170
	v_rcp_f32_e32 v171, v171
	v_pk_mul_f32 v[164:165], v[164:165], v[190:191] op_sel_hi:[1,0]
	v_pk_mul_f32 v[166:167], v[166:167], v[190:191] op_sel_hi:[1,0]
	v_pk_mul_f32 v[168:169], v[168:169], v[190:191] op_sel_hi:[1,0]
	v_pk_mul_f32 v[170:171], v[170:171], v[190:191] op_sel_hi:[1,0]
	v_pk_mul_f32 v[126:127], v[118:119], v[126:127]
	v_pk_mul_f32 v[128:129], v[120:121], v[128:129]
	v_pk_mul_f32 v[122:123], v[114:115], v[122:123]
	v_pk_mul_f32 v[124:125], v[116:117], v[124:125]
	v_pk_mul_f32 v[126:127], v[126:127], v[164:165]
	v_pk_mul_f32 v[128:129], v[128:129], v[166:167]
	v_pk_mul_f32 v[122:123], v[122:123], v[168:169]
	v_pk_mul_f32 v[124:125], v[124:125], v[170:171]
	v_cvt_pk_f16_f32 v176, v126, v127
	v_cvt_pk_f16_f32 v177, v128, v129
	v_cvt_pk_f16_f32 v178, v122, v123
	v_cvt_pk_f16_f32 v179, v124, v125
	global_store_dwordx4 v174, v[176:179], s[6:7]
	v_add_u32_e32 v174, s98, v174
	v_mul_f32_e32 v188, 0xbfb8aa3b, v181
	v_mul_f32_e32 v190, v181, v181
	v_pk_mul_f32 v[164:165], v[102:103], v[188:189] op_sel_hi:[1,0]
	v_pk_mul_f32 v[166:167], v[104:105], v[188:189] op_sel_hi:[1,0]
	v_pk_mul_f32 v[168:169], v[98:99], v[188:189] op_sel_hi:[1,0]
	v_pk_mul_f32 v[170:171], v[100:101], v[188:189] op_sel_hi:[1,0]
	v_exp_f32_e32 v164, v164
	v_exp_f32_e32 v165, v165
	v_exp_f32_e32 v166, v166
	v_exp_f32_e32 v167, v167
	v_exp_f32_e32 v168, v168
	v_exp_f32_e32 v169, v169
	v_exp_f32_e32 v170, v170
	v_exp_f32_e32 v171, v171
	v_pk_add_f32 v[164:165], v[164:165], v[192:193]
	v_pk_add_f32 v[166:167], v[166:167], v[192:193]
	v_pk_add_f32 v[168:169], v[168:169], v[192:193]
	v_pk_add_f32 v[170:171], v[170:171], v[192:193]
	v_rcp_f32_e32 v164, v164
	v_rcp_f32_e32 v165, v165
	v_rcp_f32_e32 v166, v166
	v_rcp_f32_e32 v167, v167
	v_rcp_f32_e32 v168, v168
	v_rcp_f32_e32 v169, v169
	v_rcp_f32_e32 v170, v170
	v_rcp_f32_e32 v171, v171
	v_pk_mul_f32 v[164:165], v[164:165], v[190:191] op_sel_hi:[1,0]
	v_pk_mul_f32 v[166:167], v[166:167], v[190:191] op_sel_hi:[1,0]
	v_pk_mul_f32 v[168:169], v[168:169], v[190:191] op_sel_hi:[1,0]
	v_pk_mul_f32 v[170:171], v[170:171], v[190:191] op_sel_hi:[1,0]
	v_pk_mul_f32 v[110:111], v[102:103], v[110:111]
	v_pk_mul_f32 v[112:113], v[104:105], v[112:113]
	v_pk_mul_f32 v[106:107], v[98:99], v[106:107]
	v_pk_mul_f32 v[108:109], v[100:101], v[108:109]
	v_pk_mul_f32 v[110:111], v[110:111], v[164:165]
	v_pk_mul_f32 v[112:113], v[112:113], v[166:167]
	v_pk_mul_f32 v[106:107], v[106:107], v[168:169]
	v_pk_mul_f32 v[108:109], v[108:109], v[170:171]
	v_cvt_pk_f16_f32 v176, v110, v111
	v_cvt_pk_f16_f32 v177, v112, v113
	v_cvt_pk_f16_f32 v178, v106, v107
	v_cvt_pk_f16_f32 v179, v108, v109
	global_store_dwordx4 v174, v[176:179], s[6:7]
	v_add_u32_e32 v174, s98, v174
	v_mul_f32_e32 v188, 0xbfb8aa3b, v182
	v_mul_f32_e32 v190, v182, v182
	v_pk_mul_f32 v[164:165], v[86:87], v[188:189] op_sel_hi:[1,0]
	v_pk_mul_f32 v[166:167], v[88:89], v[188:189] op_sel_hi:[1,0]
	v_pk_mul_f32 v[168:169], v[82:83], v[188:189] op_sel_hi:[1,0]
	v_pk_mul_f32 v[170:171], v[84:85], v[188:189] op_sel_hi:[1,0]
	v_exp_f32_e32 v164, v164
	v_exp_f32_e32 v165, v165
	v_exp_f32_e32 v166, v166
	v_exp_f32_e32 v167, v167
	v_exp_f32_e32 v168, v168
	v_exp_f32_e32 v169, v169
	v_exp_f32_e32 v170, v170
	v_exp_f32_e32 v171, v171
	v_pk_add_f32 v[164:165], v[164:165], v[192:193]
	v_pk_add_f32 v[166:167], v[166:167], v[192:193]
	v_pk_add_f32 v[168:169], v[168:169], v[192:193]
	v_pk_add_f32 v[170:171], v[170:171], v[192:193]
	v_rcp_f32_e32 v164, v164
	v_rcp_f32_e32 v165, v165
	v_rcp_f32_e32 v166, v166
	v_rcp_f32_e32 v167, v167
	v_rcp_f32_e32 v168, v168
	v_rcp_f32_e32 v169, v169
	v_rcp_f32_e32 v170, v170
	v_rcp_f32_e32 v171, v171
	v_pk_mul_f32 v[164:165], v[164:165], v[190:191] op_sel_hi:[1,0]
	v_pk_mul_f32 v[166:167], v[166:167], v[190:191] op_sel_hi:[1,0]
	v_pk_mul_f32 v[168:169], v[168:169], v[190:191] op_sel_hi:[1,0]
	v_pk_mul_f32 v[170:171], v[170:171], v[190:191] op_sel_hi:[1,0]
; __device__ __forceinline__ unsigned cvt_pk_bf16(float lo, float hi) { unsigned r; asm volatile("v_cvt_pk_f16_f32 %0, %1, %2" : "=v"(r) : "v"(lo), "v"(hi)); return r; }
;     __device__ __forceinline__ void operator()(const f32x4 (&acc)[2][2][4][2], const Unit& u, int wr, int wc, int fr, int fq) const {
;     ...
;             for (int m = 0; m < 4; ++m) {
;                 const int row = row0 + ai * HALF + m * 16; const float sc = rs[row];
;                 const float sc2 = sc * sc, nsl = -1.4426950408889634f * sc;
;                 bf16_t* rowp = O + (size_t)row * ldc + col0;
;                 float h[8];
; #pragma unroll
;                 for (int n = 0; n < 2; ++n)
; #pragma unroll
;                     for (int e = 0; e < 4; ++e) { const float g = acc[ai][0][m][n][e], up = acc[ai][1][m][n][e];
;                         h[4 * n + e] = (g * up) * (sc2 * __builtin_amdgcn_rcpf(1.0f + __builtin_amdgcn_exp2f(g * nsl))); }
;                 u32x4 w; w.x = cvt_pk_bf16(h[0], h[1]); w.y = cvt_pk_bf16(h[2], h[3]); w.z = cvt_pk_bf16(h[4], h[5]); w.w = cvt_pk_bf16(h[6], h[7]);
;                 *(u32x4*)rowp = w;
	v_pk_mul_f32 v[94:95], v[86:87], v[94:95]
	v_pk_mul_f32 v[96:97], v[88:89], v[96:97]
	v_pk_mul_f32 v[90:91], v[82:83], v[90:91]
	v_pk_mul_f32 v[92:93], v[84:85], v[92:93]
	v_pk_mul_f32 v[94:95], v[94:95], v[164:165]
	v_pk_mul_f32 v[96:97], v[96:97], v[166:167]
	v_pk_mul_f32 v[90:91], v[90:91], v[168:169]
	v_pk_mul_f32 v[92:93], v[92:93], v[170:171]
	v_cvt_pk_f16_f32 v176, v94, v95
	v_cvt_pk_f16_f32 v177, v96, v97
	v_cvt_pk_f16_f32 v178, v90, v91
	v_cvt_pk_f16_f32 v179, v92, v93
	global_store_dwordx4 v174, v[176:179], s[6:7]
	v_add_u32_e32 v174, s98, v174
	v_mul_f32_e32 v188, 0xbfb8aa3b, v183
	v_mul_f32_e32 v190, v183, v183
	v_pk_mul_f32 v[164:165], v[70:71], v[188:189] op_sel_hi:[1,0]
	v_pk_mul_f32 v[166:167], v[72:73], v[188:189] op_sel_hi:[1,0]
	v_pk_mul_f32 v[168:169], v[66:67], v[188:189] op_sel_hi:[1,0]
	v_pk_mul_f32 v[170:171], v[68:69], v[188:189] op_sel_hi:[1,0]
	v_exp_f32_e32 v164, v164
	v_exp_f32_e32 v165, v165
	v_exp_f32_e32 v166, v166
	v_exp_f32_e32 v167, v167
	v_exp_f32_e32 v168, v168
	v_exp_f32_e32 v169, v169
	v_exp_f32_e32 v170, v170
	v_exp_f32_e32 v171, v171
	v_pk_add_f32 v[164:165], v[164:165], v[192:193]
	v_pk_add_f32 v[166:167], v[166:167], v[192:193]
	v_pk_add_f32 v[168:169], v[168:169], v[192:193]
	v_pk_add_f32 v[170:171], v[170:171], v[192:193]
	v_rcp_f32_e32 v164, v164
	v_rcp_f32_e32 v165, v165
	v_rcp_f32_e32 v166, v166
	v_rcp_f32_e32 v167, v167
	v_rcp_f32_e32 v168, v168
	v_rcp_f32_e32 v169, v169
	v_rcp_f32_e32 v170, v170
	v_rcp_f32_e32 v171, v171
	v_pk_mul_f32 v[164:165], v[164:165], v[190:191] op_sel_hi:[1,0]
	v_pk_mul_f32 v[166:167], v[166:167], v[190:191] op_sel_hi:[1,0]
	v_pk_mul_f32 v[168:169], v[168:169], v[190:191] op_sel_hi:[1,0]
	v_pk_mul_f32 v[170:171], v[170:171], v[190:191] op_sel_hi:[1,0]
	v_pk_mul_f32 v[78:79], v[70:71], v[78:79]
	v_pk_mul_f32 v[80:81], v[72:73], v[80:81]
	v_pk_mul_f32 v[74:75], v[66:67], v[74:75]
	v_pk_mul_f32 v[76:77], v[68:69], v[76:77]
	v_pk_mul_f32 v[78:79], v[78:79], v[164:165]
	v_pk_mul_f32 v[80:81], v[80:81], v[166:167]
	v_pk_mul_f32 v[74:75], v[74:75], v[168:169]
	v_pk_mul_f32 v[76:77], v[76:77], v[170:171]
	v_cvt_pk_f16_f32 v176, v78, v79
	v_cvt_pk_f16_f32 v177, v80, v81
	v_cvt_pk_f16_f32 v178, v74, v75
	v_cvt_pk_f16_f32 v179, v76, v77
	global_store_dwordx4 v174, v[176:179], s[6:7]
	v_mul_f32_e32 v188, 0xbfb8aa3b, v184
	v_mul_f32_e32 v190, v184, v184
	v_pk_mul_f32 v[164:165], v[54:55], v[188:189] op_sel_hi:[1,0]
	v_pk_mul_f32 v[166:167], v[56:57], v[188:189] op_sel_hi:[1,0]
	v_pk_mul_f32 v[168:169], v[50:51], v[188:189] op_sel_hi:[1,0]
	v_pk_mul_f32 v[170:171], v[52:53], v[188:189] op_sel_hi:[1,0]
	v_exp_f32_e32 v164, v164
	v_exp_f32_e32 v165, v165
	v_exp_f32_e32 v166, v166
	v_exp_f32_e32 v167, v167
	v_exp_f32_e32 v168, v168
	v_exp_f32_e32 v169, v169
	v_exp_f32_e32 v170, v170
	v_exp_f32_e32 v171, v171
	v_pk_add_f32 v[164:165], v[164:165], v[192:193]
	v_pk_add_f32 v[166:167], v[166:167], v[192:193]
	v_pk_add_f32 v[168:169], v[168:169], v[192:193]
	v_pk_add_f32 v[170:171], v[170:171], v[192:193]
	v_rcp_f32_e32 v164, v164
	v_rcp_f32_e32 v165, v165
	v_rcp_f32_e32 v166, v166
	v_rcp_f32_e32 v167, v167
	v_rcp_f32_e32 v168, v168
	v_rcp_f32_e32 v169, v169
	v_rcp_f32_e32 v170, v170
	v_rcp_f32_e32 v171, v171
	v_pk_mul_f32 v[164:165], v[164:165], v[190:191] op_sel_hi:[1,0]
	v_pk_mul_f32 v[166:167], v[166:167], v[190:191] op_sel_hi:[1,0]
	v_pk_mul_f32 v[168:169], v[168:169], v[190:191] op_sel_hi:[1,0]
	v_pk_mul_f32 v[170:171], v[170:171], v[190:191] op_sel_hi:[1,0]
	v_pk_mul_f32 v[62:63], v[54:55], v[62:63]
	v_pk_mul_f32 v[64:65], v[56:57], v[64:65]
	v_pk_mul_f32 v[58:59], v[50:51], v[58:59]
	v_pk_mul_f32 v[60:61], v[52:53], v[60:61]
	v_pk_mul_f32 v[62:63], v[62:63], v[164:165]
	v_pk_mul_f32 v[64:65], v[64:65], v[166:167]
	v_pk_mul_f32 v[58:59], v[58:59], v[168:169]
	v_pk_mul_f32 v[60:61], v[60:61], v[170:171]
	v_cvt_pk_f16_f32 v176, v62, v63
	v_cvt_pk_f16_f32 v177, v64, v65
	v_cvt_pk_f16_f32 v178, v58, v59
	v_cvt_pk_f16_f32 v179, v60, v61
	global_store_dwordx4 v175, v[176:179], s[6:7]
	v_add_u32_e32 v175, s98, v175
	v_mul_f32_e32 v188, 0xbfb8aa3b, v185
	v_mul_f32_e32 v190, v185, v185
	v_pk_mul_f32 v[164:165], v[38:39], v[188:189] op_sel_hi:[1,0]
	v_pk_mul_f32 v[166:167], v[40:41], v[188:189] op_sel_hi:[1,0]
	v_pk_mul_f32 v[168:169], v[34:35], v[188:189] op_sel_hi:[1,0]
	v_pk_mul_f32 v[170:171], v[36:37], v[188:189] op_sel_hi:[1,0]
	v_exp_f32_e32 v164, v164
	v_exp_f32_e32 v165, v165
	v_exp_f32_e32 v166, v166
	v_exp_f32_e32 v167, v167
	v_exp_f32_e32 v168, v168
	v_exp_f32_e32 v169, v169
	v_exp_f32_e32 v170, v170
	v_exp_f32_e32 v171, v171
	v_pk_add_f32 v[164:165], v[164:165], v[192:193]
	v_pk_add_f32 v[166:167], v[166:167], v[192:193]
; __device__ __forceinline__ unsigned cvt_pk_bf16(float lo, float hi) { unsigned r; asm volatile("v_cvt_pk_f16_f32 %0, %1, %2" : "=v"(r) : "v"(lo), "v"(hi)); return r; }
;     __device__ __forceinline__ void operator()(const f32x4 (&acc)[2][2][4][2], const Unit& u, int wr, int wc, int fr, int fq) const {
;     ...
;             for (int m = 0; m < 4; ++m) {
;                 const int row = row0 + ai * HALF + m * 16; const float sc = rs[row];
;                 const float sc2 = sc * sc, nsl = -1.4426950408889634f * sc;
;                 bf16_t* rowp = O + (size_t)row * ldc + col0;
;                 float h[8];
; #pragma unroll
;                 for (int n = 0; n < 2; ++n)
; #pragma unroll
;                     for (int e = 0; e < 4; ++e) { const float g = acc[ai][0][m][n][e], up = acc[ai][1][m][n][e];
;                         h[4 * n + e] = (g * up) * (sc2 * __builtin_amdgcn_rcpf(1.0f + __builtin_amdgcn_exp2f(g * nsl))); }
;                 u32x4 w; w.x = cvt_pk_bf16(h[0], h[1]); w.y = cvt_pk_bf16(h[2], h[3]); w.z = cvt_pk_bf16(h[4], h[5]); w.w = cvt_pk_bf16(h[6], h[7]);
;                 *(u32x4*)rowp = w;
;             }
;     }
	v_pk_add_f32 v[168:169], v[168:169], v[192:193]
	v_pk_add_f32 v[170:171], v[170:171], v[192:193]
	v_rcp_f32_e32 v164, v164
	v_rcp_f32_e32 v165, v165
	v_rcp_f32_e32 v166, v166
	v_rcp_f32_e32 v167, v167
	v_rcp_f32_e32 v168, v168
	v_rcp_f32_e32 v169, v169
	v_rcp_f32_e32 v170, v170
	v_rcp_f32_e32 v171, v171
	v_pk_mul_f32 v[164:165], v[164:165], v[190:191] op_sel_hi:[1,0]
	v_pk_mul_f32 v[166:167], v[166:167], v[190:191] op_sel_hi:[1,0]
	v_pk_mul_f32 v[168:169], v[168:169], v[190:191] op_sel_hi:[1,0]
	v_pk_mul_f32 v[170:171], v[170:171], v[190:191] op_sel_hi:[1,0]
	v_pk_mul_f32 v[46:47], v[38:39], v[46:47]
	v_pk_mul_f32 v[48:49], v[40:41], v[48:49]
	v_pk_mul_f32 v[42:43], v[34:35], v[42:43]
	v_pk_mul_f32 v[44:45], v[36:37], v[44:45]
	v_pk_mul_f32 v[46:47], v[46:47], v[164:165]
	v_pk_mul_f32 v[48:49], v[48:49], v[166:167]
	v_pk_mul_f32 v[42:43], v[42:43], v[168:169]
	v_pk_mul_f32 v[44:45], v[44:45], v[170:171]
	v_cvt_pk_f16_f32 v176, v46, v47
	v_cvt_pk_f16_f32 v177, v48, v49
	v_cvt_pk_f16_f32 v178, v42, v43
	v_cvt_pk_f16_f32 v179, v44, v45
	global_store_dwordx4 v175, v[176:179], s[6:7]
	v_add_u32_e32 v175, s98, v175
	v_mul_f32_e32 v188, 0xbfb8aa3b, v186
	v_mul_f32_e32 v190, v186, v186
	v_pk_mul_f32 v[164:165], v[22:23], v[188:189] op_sel_hi:[1,0]
	v_pk_mul_f32 v[166:167], v[24:25], v[188:189] op_sel_hi:[1,0]
	v_pk_mul_f32 v[168:169], v[18:19], v[188:189] op_sel_hi:[1,0]
	v_pk_mul_f32 v[170:171], v[20:21], v[188:189] op_sel_hi:[1,0]
	v_exp_f32_e32 v164, v164
	v_exp_f32_e32 v165, v165
	v_exp_f32_e32 v166, v166
	v_exp_f32_e32 v167, v167
	v_exp_f32_e32 v168, v168
	v_exp_f32_e32 v169, v169
	v_exp_f32_e32 v170, v170
	v_exp_f32_e32 v171, v171
	v_pk_add_f32 v[164:165], v[164:165], v[192:193]
	v_pk_add_f32 v[166:167], v[166:167], v[192:193]
	v_pk_add_f32 v[168:169], v[168:169], v[192:193]
	v_pk_add_f32 v[170:171], v[170:171], v[192:193]
	v_rcp_f32_e32 v164, v164
	v_rcp_f32_e32 v165, v165
	v_rcp_f32_e32 v166, v166
	v_rcp_f32_e32 v167, v167
	v_rcp_f32_e32 v168, v168
	v_rcp_f32_e32 v169, v169
	v_rcp_f32_e32 v170, v170
	v_rcp_f32_e32 v171, v171
	v_pk_mul_f32 v[164:165], v[164:165], v[190:191] op_sel_hi:[1,0]
	v_pk_mul_f32 v[166:167], v[166:167], v[190:191] op_sel_hi:[1,0]
	v_pk_mul_f32 v[168:169], v[168:169], v[190:191] op_sel_hi:[1,0]
	v_pk_mul_f32 v[170:171], v[170:171], v[190:191] op_sel_hi:[1,0]
	v_pk_mul_f32 v[30:31], v[22:23], v[30:31]
	v_pk_mul_f32 v[32:33], v[24:25], v[32:33]
	v_pk_mul_f32 v[26:27], v[18:19], v[26:27]
	v_pk_mul_f32 v[28:29], v[20:21], v[28:29]
	v_pk_mul_f32 v[30:31], v[30:31], v[164:165]
	v_pk_mul_f32 v[32:33], v[32:33], v[166:167]
	v_pk_mul_f32 v[26:27], v[26:27], v[168:169]
	v_pk_mul_f32 v[28:29], v[28:29], v[170:171]
	v_cvt_pk_f16_f32 v176, v30, v31
	v_cvt_pk_f16_f32 v177, v32, v33
	v_cvt_pk_f16_f32 v178, v26, v27
	v_cvt_pk_f16_f32 v179, v28, v29
	global_store_dwordx4 v175, v[176:179], s[6:7]
	v_add_u32_e32 v175, s98, v175
	v_mul_f32_e32 v188, 0xbfb8aa3b, v187
	v_mul_f32_e32 v190, v187, v187
	v_pk_mul_f32 v[164:165], v[6:7], v[188:189] op_sel_hi:[1,0]
	v_pk_mul_f32 v[166:167], v[8:9], v[188:189] op_sel_hi:[1,0]
	v_pk_mul_f32 v[168:169], v[2:3], v[188:189] op_sel_hi:[1,0]
	v_pk_mul_f32 v[170:171], v[4:5], v[188:189] op_sel_hi:[1,0]
	v_exp_f32_e32 v164, v164
	v_exp_f32_e32 v165, v165
	v_exp_f32_e32 v166, v166
	v_exp_f32_e32 v167, v167
	v_exp_f32_e32 v168, v168
	v_exp_f32_e32 v169, v169
	v_exp_f32_e32 v170, v170
	v_exp_f32_e32 v171, v171
	v_pk_add_f32 v[164:165], v[164:165], v[192:193]
	v_pk_add_f32 v[166:167], v[166:167], v[192:193]
	v_pk_add_f32 v[168:169], v[168:169], v[192:193]
	v_pk_add_f32 v[170:171], v[170:171], v[192:193]
	v_rcp_f32_e32 v164, v164
	v_rcp_f32_e32 v165, v165
	v_rcp_f32_e32 v166, v166
	v_rcp_f32_e32 v167, v167
	v_rcp_f32_e32 v168, v168
	v_rcp_f32_e32 v169, v169
	v_rcp_f32_e32 v170, v170
	v_rcp_f32_e32 v171, v171
	v_pk_mul_f32 v[164:165], v[164:165], v[190:191] op_sel_hi:[1,0]
	v_pk_mul_f32 v[166:167], v[166:167], v[190:191] op_sel_hi:[1,0]
	v_pk_mul_f32 v[168:169], v[168:169], v[190:191] op_sel_hi:[1,0]
	v_pk_mul_f32 v[170:171], v[170:171], v[190:191] op_sel_hi:[1,0]
	v_pk_mul_f32 v[14:15], v[6:7], v[14:15]
	v_pk_mul_f32 v[16:17], v[8:9], v[16:17]
	v_pk_mul_f32 v[10:11], v[2:3], v[10:11]
	v_pk_mul_f32 v[12:13], v[4:5], v[12:13]
	v_pk_mul_f32 v[14:15], v[14:15], v[164:165]
	v_pk_mul_f32 v[16:17], v[16:17], v[166:167]
	v_pk_mul_f32 v[10:11], v[10:11], v[168:169]
	v_pk_mul_f32 v[12:13], v[12:13], v[170:171]
	v_cvt_pk_f16_f32 v176, v14, v15
	v_cvt_pk_f16_f32 v177, v16, v17
	v_cvt_pk_f16_f32 v178, v10, v11
	v_cvt_pk_f16_f32 v179, v12, v13
	global_store_dwordx4 v175, v[176:179], s[6:7]
	s_cbranch_vccnz .LBB0_162
	s_andn2_b64 vcc, exec, s[4:5]
	s_cbranch_vccnz .LBB0_161
	s_barrier
	s_branch .LBB0_161

; __device__ __forceinline__ unsigned cvt_pk_bf16(float lo, float hi) { unsigned r; asm volatile("v_cvt_pk_f16_f32 %0, %1, %2" : "=v"(r) : "v"(lo), "v"(hi)); return r; }
;     __device__ __forceinline__ void operator()(const f32x4 (&acc)[2][2][4][2], const Unit& u, int wr, int wc, int fr, int fq) const {
;         const int row0 = u.pm * BM + wr * 64 + fr, col0 = u.pn * HALF + wc * 32 + 8 * fq;
; #pragma unroll
;         for (int ai = 0; ai < 2; ++ai)
; #pragma unroll
;             for (int m = 0; m < 4; ++m) {
;                 const int row = row0 + ai * HALF + m * 16; const float sc = rs[row];
;                 const float sc2 = sc * sc, nsl = -1.4426950408889634f * sc;
;                 bf16_t* rowp = O + (size_t)row * ldc + col0;
;                 float h[8];
; #pragma unroll
;                 for (int n = 0; n < 2; ++n)
; #pragma unroll
;                     for (int e = 0; e < 4; ++e) { const float g = acc[ai][0][m][n][e], up = acc[ai][1][m][n][e];
;                         h[4 * n + e] = (g * up) * (sc2 * __builtin_amdgcn_rcpf(1.0f + __builtin_amdgcn_exp2f(g * nsl))); }
;                 u32x4 w; w.x = cvt_pk_bf16(h[0], h[1]); w.y = cvt_pk_bf16(h[2], h[3]); w.z = cvt_pk_bf16(h[4], h[5]); w.w = cvt_pk_bf16(h[6], h[7]);
;                 *(u32x4*)rowp = w;
;             }
;     }
.LBB0_1017:
	v_lshl_add_u32 v146, s22, 8, v1
	v_ashrrev_i32_e32 v147, 31, v146
	v_lshl_add_u64 v[150:151], v[146:147], 2, s[8:9]
	global_load_dword v180, v[150:151], off
	global_load_dword v181, v[150:151], off offset:64
	global_load_dword v182, v[150:151], off offset:128
	global_load_dword v183, v[150:151], off offset:192
	global_load_dword v184, v[150:151], off offset:512
	global_load_dword v185, v[150:151], off offset:576
	global_load_dword v186, v[150:151], off offset:640
	global_load_dword v187, v[150:151], off offset:704
	v_lshl_or_b32 v158, s47, 7, v153
	v_lshlrev_b32_e32 v159, 1, v158
	v_mad_u32_u24 v174, v146, s46, v159
	s_lshl_b32 s98, s46, 4
	s_lshl_b32 s99, s46, 7
	v_mov_b32_e32 v192, 1.0
	v_mov_b32_e32 v193, 1.0
	v_add_u32_e32 v175, s99, v174
	s_andn2_b64 vcc, exec, s[2:3]
	s_mov_b64 s[2:3], -1
	s_waitcnt vmcnt(0)
	v_mul_f32_e32 v188, 0xbfb8aa3b, v180
	v_mul_f32_e32 v190, v180, v180
	v_pk_mul_f32 v[164:165], v[118:119], v[188:189] op_sel_hi:[1,0]
	v_pk_mul_f32 v[166:167], v[120:121], v[188:189] op_sel_hi:[1,0]
	v_pk_mul_f32 v[168:169], v[114:115], v[188:189] op_sel_hi:[1,0]
	v_pk_mul_f32 v[170:171], v[116:117], v[188:189] op_sel_hi:[1,0]
	v_exp_f32_e32 v164, v164
	v_exp_f32_e32 v165, v165
	v_exp_f32_e32 v166, v166
	v_exp_f32_e32 v167, v167
	v_exp_f32_e32 v168, v168
	v_exp_f32_e32 v169, v169
	v_exp_f32_e32 v170, v170
	v_exp_f32_e32 v171, v171
	v_pk_add_f32 v[164:165], v[164:165], v[192:193]
	v_pk_add_f32 v[166:167], v[166:167], v[192:193]
	v_pk_add_f32 v[168:169], v[168:169], v[192:193]
	v_pk_add_f32 v[170:171], v[170:171], v[192:193]
	v_rcp_f32_e32 v164, v164
	v_rcp_f32_e32 v165, v165
	v_rcp_f32_e32 v166, v166
	v_rcp_f32_e32 v167, v167
	v_rcp_f32_e32 v168, v168
	v_rcp_f32_e32 v169, v169
	v_rcp_f32_e32 v170, v170
	v_rcp_f32_e32 v171, v171
	v_pk_mul_f32 v[164:165], v[164:165], v[190:191] op_sel_hi:[1,0]
	v_pk_mul_f32 v[166:167], v[166:167], v[190:191] op_sel_hi:[1,0]
	v_pk_mul_f32 v[168:169], v[168:169], v[190:191] op_sel_hi:[1,0]
	v_pk_mul_f32 v[170:171], v[170:171], v[190:191] op_sel_hi:[1,0]
	v_pk_mul_f32 v[126:127], v[118:119], v[126:127]
	v_pk_mul_f32 v[128:129], v[120:121], v[128:129]
	v_pk_mul_f32 v[122:123], v[114:115], v[122:123]
	v_pk_mul_f32 v[124:125], v[116:117], v[124:125]
	v_pk_mul_f32 v[126:127], v[126:127], v[164:165]
	v_pk_mul_f32 v[128:129], v[128:129], v[166:167]
	v_pk_mul_f32 v[122:123], v[122:123], v[168:169]
	v_pk_mul_f32 v[124:125], v[124:125], v[170:171]
	v_cvt_pk_f16_f32 v176, v126, v127
	v_cvt_pk_f16_f32 v177, v128, v129
	v_cvt_pk_f16_f32 v178, v122, v123
	v_cvt_pk_f16_f32 v179, v124, v125
	global_store_dwordx4 v174, v[176:179], s[6:7]
	v_add_u32_e32 v174, s98, v174
	v_mul_f32_e32 v188, 0xbfb8aa3b, v181
	v_mul_f32_e32 v190, v181, v181
	v_pk_mul_f32 v[164:165], v[102:103], v[188:189] op_sel_hi:[1,0]
	v_pk_mul_f32 v[166:167], v[104:105], v[188:189] op_sel_hi:[1,0]
	v_pk_mul_f32 v[168:169], v[98:99], v[188:189] op_sel_hi:[1,0]
	v_pk_mul_f32 v[170:171], v[100:101], v[188:189] op_sel_hi:[1,0]
	v_exp_f32_e32 v164, v164
	v_exp_f32_e32 v165, v165
	v_exp_f32_e32 v166, v166
	v_exp_f32_e32 v167, v167
	v_exp_f32_e32 v168, v168
	v_exp_f32_e32 v169, v169
	v_exp_f32_e32 v170, v170
	v_exp_f32_e32 v171, v171
	v_pk_add_f32 v[164:165], v[164:165], v[192:193]
	v_pk_add_f32 v[166:167], v[166:167], v[192:193]
	v_pk_add_f32 v[168:169], v[168:169], v[192:193]
	v_pk_add_f32 v[170:171], v[170:171], v[192:193]
	v_rcp_f32_e32 v164, v164
	v_rcp_f32_e32 v165, v165
	v_rcp_f32_e32 v166, v166
	v_rcp_f32_e32 v167, v167
	v_rcp_f32_e32 v168, v168
	v_rcp_f32_e32 v169, v169
	v_rcp_f32_e32 v170, v170
	v_rcp_f32_e32 v171, v171
	v_pk_mul_f32 v[164:165], v[164:165], v[190:191] op_sel_hi:[1,0]
	v_pk_mul_f32 v[166:167], v[166:167], v[190:191] op_sel_hi:[1,0]
	v_pk_mul_f32 v[168:169], v[168:169], v[190:191] op_sel_hi:[1,0]
	v_pk_mul_f32 v[170:171], v[170:171], v[190:191] op_sel_hi:[1,0]
	v_pk_mul_f32 v[110:111], v[102:103], v[110:111]
	v_pk_mul_f32 v[112:113], v[104:105], v[112:113]
	v_pk_mul_f32 v[106:107], v[98:99], v[106:107]
	v_pk_mul_f32 v[108:109], v[100:101], v[108:109]
	v_pk_mul_f32 v[110:111], v[110:111], v[164:165]
	v_pk_mul_f32 v[112:113], v[112:113], v[166:167]
	v_pk_mul_f32 v[106:107], v[106:107], v[168:169]
	v_pk_mul_f32 v[108:109], v[108:109], v[170:171]
	v_cvt_pk_f16_f32 v176, v110, v111
	v_cvt_pk_f16_f32 v177, v112, v113
	v_cvt_pk_f16_f32 v178, v106, v107
	v_cvt_pk_f16_f32 v179, v108, v109
	global_store_dwordx4 v174, v[176:179], s[6:7]
	v_add_u32_e32 v174, s98, v174
	v_mul_f32_e32 v188, 0xbfb8aa3b, v182
	v_mul_f32_e32 v190, v182, v182
	v_pk_mul_f32 v[164:165], v[86:87], v[188:189] op_sel_hi:[1,0]
	v_pk_mul_f32 v[166:167], v[88:89], v[188:189] op_sel_hi:[1,0]
	v_pk_mul_f32 v[168:169], v[82:83], v[188:189] op_sel_hi:[1,0]
	v_pk_mul_f32 v[170:171], v[84:85], v[188:189] op_sel_hi:[1,0]
	v_exp_f32_e32 v164, v164
	v_exp_f32_e32 v165, v165
	v_exp_f32_e32 v166, v166
	v_exp_f32_e32 v167, v167
	v_exp_f32_e32 v168, v168
	v_exp_f32_e32 v169, v169
	v_exp_f32_e32 v170, v170
	v_exp_f32_e32 v171, v171
	v_pk_add_f32 v[164:165], v[164:165], v[192:193]
	v_pk_add_f32 v[166:167], v[166:167], v[192:193]
	v_pk_add_f32 v[168:169], v[168:169], v[192:193]
	v_pk_add_f32 v[170:171], v[170:171], v[192:193]
	v_rcp_f32_e32 v164, v164
	v_rcp_f32_e32 v165, v165
	v_rcp_f32_e32 v166, v166
	v_rcp_f32_e32 v167, v167
	v_rcp_f32_e32 v168, v168
	v_rcp_f32_e32 v169, v169
	v_rcp_f32_e32 v170, v170
	v_rcp_f32_e32 v171, v171
	v_pk_mul_f32 v[164:165], v[164:165], v[190:191] op_sel_hi:[1,0]
	v_pk_mul_f32 v[166:167], v[166:167], v[190:191] op_sel_hi:[1,0]
	v_pk_mul_f32 v[168:169], v[168:169], v[190:191] op_sel_hi:[1,0]
	v_pk_mul_f32 v[170:171], v[170:171], v[190:191] op_sel_hi:[1,0]
; __device__ __forceinline__ unsigned cvt_pk_bf16(float lo, float hi) { unsigned r; asm volatile("v_cvt_pk_f16_f32 %0, %1, %2" : "=v"(r) : "v"(lo), "v"(hi)); return r; }
;     __device__ __forceinline__ void operator()(const f32x4 (&acc)[2][2][4][2], const Unit& u, int wr, int wc, int fr, int fq) const {
;     ...
;             for (int m = 0; m < 4; ++m) {
;                 const int row = row0 + ai * HALF + m * 16; const float sc = rs[row];
;                 const float sc2 = sc * sc, nsl = -1.4426950408889634f * sc;
;                 bf16_t* rowp = O + (size_t)row * ldc + col0;
;                 float h[8];
; #pragma unroll
;                 for (int n = 0; n < 2; ++n)
; #pragma unroll
;                     for (int e = 0; e < 4; ++e) { const float g = acc[ai][0][m][n][e], up = acc[ai][1][m][n][e];
;                         h[4 * n + e] = (g * up) * (sc2 * __builtin_amdgcn_rcpf(1.0f + __builtin_amdgcn_exp2f(g * nsl))); }
;                 u32x4 w; w.x = cvt_pk_bf16(h[0], h[1]); w.y = cvt_pk_bf16(h[2], h[3]); w.z = cvt_pk_bf16(h[4], h[5]); w.w = cvt_pk_bf16(h[6], h[7]);
;                 *(u32x4*)rowp = w;
	v_pk_mul_f32 v[94:95], v[86:87], v[94:95]
	v_pk_mul_f32 v[96:97], v[88:89], v[96:97]
	v_pk_mul_f32 v[90:91], v[82:83], v[90:91]
	v_pk_mul_f32 v[92:93], v[84:85], v[92:93]
	v_pk_mul_f32 v[94:95], v[94:95], v[164:165]
	v_pk_mul_f32 v[96:97], v[96:97], v[166:167]
	v_pk_mul_f32 v[90:91], v[90:91], v[168:169]
	v_pk_mul_f32 v[92:93], v[92:93], v[170:171]
	v_cvt_pk_f16_f32 v176, v94, v95
	v_cvt_pk_f16_f32 v177, v96, v97
	v_cvt_pk_f16_f32 v178, v90, v91
	v_cvt_pk_f16_f32 v179, v92, v93
	global_store_dwordx4 v174, v[176:179], s[6:7]
	v_add_u32_e32 v174, s98, v174
	v_mul_f32_e32 v188, 0xbfb8aa3b, v183
	v_mul_f32_e32 v190, v183, v183
	v_pk_mul_f32 v[164:165], v[70:71], v[188:189] op_sel_hi:[1,0]
	v_pk_mul_f32 v[166:167], v[72:73], v[188:189] op_sel_hi:[1,0]
	v_pk_mul_f32 v[168:169], v[66:67], v[188:189] op_sel_hi:[1,0]
	v_pk_mul_f32 v[170:171], v[68:69], v[188:189] op_sel_hi:[1,0]
	v_exp_f32_e32 v164, v164
	v_exp_f32_e32 v165, v165
	v_exp_f32_e32 v166, v166
	v_exp_f32_e32 v167, v167
	v_exp_f32_e32 v168, v168
	v_exp_f32_e32 v169, v169
	v_exp_f32_e32 v170, v170
	v_exp_f32_e32 v171, v171
	v_pk_add_f32 v[164:165], v[164:165], v[192:193]
	v_pk_add_f32 v[166:167], v[166:167], v[192:193]
	v_pk_add_f32 v[168:169], v[168:169], v[192:193]
	v_pk_add_f32 v[170:171], v[170:171], v[192:193]
	v_rcp_f32_e32 v164, v164
	v_rcp_f32_e32 v165, v165
	v_rcp_f32_e32 v166, v166
	v_rcp_f32_e32 v167, v167
	v_rcp_f32_e32 v168, v168
	v_rcp_f32_e32 v169, v169
	v_rcp_f32_e32 v170, v170
	v_rcp_f32_e32 v171, v171
	v_pk_mul_f32 v[164:165], v[164:165], v[190:191] op_sel_hi:[1,0]
	v_pk_mul_f32 v[166:167], v[166:167], v[190:191] op_sel_hi:[1,0]
	v_pk_mul_f32 v[168:169], v[168:169], v[190:191] op_sel_hi:[1,0]
	v_pk_mul_f32 v[170:171], v[170:171], v[190:191] op_sel_hi:[1,0]
	v_pk_mul_f32 v[78:79], v[70:71], v[78:79]
	v_pk_mul_f32 v[80:81], v[72:73], v[80:81]
	v_pk_mul_f32 v[74:75], v[66:67], v[74:75]
	v_pk_mul_f32 v[76:77], v[68:69], v[76:77]
	v_pk_mul_f32 v[78:79], v[78:79], v[164:165]
	v_pk_mul_f32 v[80:81], v[80:81], v[166:167]
	v_pk_mul_f32 v[74:75], v[74:75], v[168:169]
	v_pk_mul_f32 v[76:77], v[76:77], v[170:171]
	v_cvt_pk_f16_f32 v176, v78, v79
	v_cvt_pk_f16_f32 v177, v80, v81
	v_cvt_pk_f16_f32 v178, v74, v75
	v_cvt_pk_f16_f32 v179, v76, v77
	global_store_dwordx4 v174, v[176:179], s[6:7]
	v_mul_f32_e32 v188, 0xbfb8aa3b, v184
	v_mul_f32_e32 v190, v184, v184
	v_pk_mul_f32 v[164:165], v[54:55], v[188:189] op_sel_hi:[1,0]
	v_pk_mul_f32 v[166:167], v[56:57], v[188:189] op_sel_hi:[1,0]
	v_pk_mul_f32 v[168:169], v[50:51], v[188:189] op_sel_hi:[1,0]
	v_pk_mul_f32 v[170:171], v[52:53], v[188:189] op_sel_hi:[1,0]
	v_exp_f32_e32 v164, v164
	v_exp_f32_e32 v165, v165
	v_exp_f32_e32 v166, v166
	v_exp_f32_e32 v167, v167
	v_exp_f32_e32 v168, v168
	v_exp_f32_e32 v169, v169
	v_exp_f32_e32 v170, v170
	v_exp_f32_e32 v171, v171
	v_pk_add_f32 v[164:165], v[164:165], v[192:193]
	v_pk_add_f32 v[166:167], v[166:167], v[192:193]
	v_pk_add_f32 v[168:169], v[168:169], v[192:193]
	v_pk_add_f32 v[170:171], v[170:171], v[192:193]
	v_rcp_f32_e32 v164, v164
	v_rcp_f32_e32 v165, v165
	v_rcp_f32_e32 v166, v166
	v_rcp_f32_e32 v167, v167
	v_rcp_f32_e32 v168, v168
	v_rcp_f32_e32 v169, v169
	v_rcp_f32_e32 v170, v170
	v_rcp_f32_e32 v171, v171
	v_pk_mul_f32 v[164:165], v[164:165], v[190:191] op_sel_hi:[1,0]
	v_pk_mul_f32 v[166:167], v[166:167], v[190:191] op_sel_hi:[1,0]
	v_pk_mul_f32 v[168:169], v[168:169], v[190:191] op_sel_hi:[1,0]
	v_pk_mul_f32 v[170:171], v[170:171], v[190:191] op_sel_hi:[1,0]
	v_pk_mul_f32 v[62:63], v[54:55], v[62:63]
	v_pk_mul_f32 v[64:65], v[56:57], v[64:65]
	v_pk_mul_f32 v[58:59], v[50:51], v[58:59]
	v_pk_mul_f32 v[60:61], v[52:53], v[60:61]
	v_pk_mul_f32 v[62:63], v[62:63], v[164:165]
	v_pk_mul_f32 v[64:65], v[64:65], v[166:167]
	v_pk_mul_f32 v[58:59], v[58:59], v[168:169]
	v_pk_mul_f32 v[60:61], v[60:61], v[170:171]
	v_cvt_pk_f16_f32 v176, v62, v63
	v_cvt_pk_f16_f32 v177, v64, v65
	v_cvt_pk_f16_f32 v178, v58, v59
	v_cvt_pk_f16_f32 v179, v60, v61
	global_store_dwordx4 v175, v[176:179], s[6:7]
	v_add_u32_e32 v175, s98, v175
	v_mul_f32_e32 v188, 0xbfb8aa3b, v185
	v_mul_f32_e32 v190, v185, v185
	v_pk_mul_f32 v[164:165], v[38:39], v[188:189] op_sel_hi:[1,0]
	v_pk_mul_f32 v[166:167], v[40:41], v[188:189] op_sel_hi:[1,0]
	v_pk_mul_f32 v[168:169], v[34:35], v[188:189] op_sel_hi:[1,0]
	v_pk_mul_f32 v[170:171], v[36:37], v[188:189] op_sel_hi:[1,0]
	v_exp_f32_e32 v164, v164
	v_exp_f32_e32 v165, v165
	v_exp_f32_e32 v166, v166
	v_exp_f32_e32 v167, v167
	v_exp_f32_e32 v168, v168
	v_exp_f32_e32 v169, v169
	v_exp_f32_e32 v170, v170
	v_exp_f32_e32 v171, v171
	v_pk_add_f32 v[164:165], v[164:165], v[192:193]
	v_pk_add_f32 v[166:167], v[166:167], v[192:193]
; __device__ __forceinline__ unsigned cvt_pk_bf16(float lo, float hi) { unsigned r; asm volatile("v_cvt_pk_f16_f32 %0, %1, %2" : "=v"(r) : "v"(lo), "v"(hi)); return r; }
;     __device__ __forceinline__ void operator()(const f32x4 (&acc)[2][2][4][2], const Unit& u, int wr, int wc, int fr, int fq) const {
;     ...
;             for (int m = 0; m < 4; ++m) {
;                 const int row = row0 + ai * HALF + m * 16; const float sc = rs[row];
;                 const float sc2 = sc * sc, nsl = -1.4426950408889634f * sc;
;                 bf16_t* rowp = O + (size_t)row * ldc + col0;
;                 float h[8];
; #pragma unroll
;                 for (int n = 0; n < 2; ++n)
; #pragma unroll
;                     for (int e = 0; e < 4; ++e) { const float g = acc[ai][0][m][n][e], up = acc[ai][1][m][n][e];
;                         h[4 * n + e] = (g * up) * (sc2 * __builtin_amdgcn_rcpf(1.0f + __builtin_amdgcn_exp2f(g * nsl))); }
;                 u32x4 w; w.x = cvt_pk_bf16(h[0], h[1]); w.y = cvt_pk_bf16(h[2], h[3]); w.z = cvt_pk_bf16(h[4], h[5]); w.w = cvt_pk_bf16(h[6], h[7]);
;                 *(u32x4*)rowp = w;
;             }
;     }
	v_pk_add_f32 v[168:169], v[168:169], v[192:193]
	v_pk_add_f32 v[170:171], v[170:171], v[192:193]
	v_rcp_f32_e32 v164, v164
	v_rcp_f32_e32 v165, v165
	v_rcp_f32_e32 v166, v166
	v_rcp_f32_e32 v167, v167
	v_rcp_f32_e32 v168, v168
	v_rcp_f32_e32 v169, v169
	v_rcp_f32_e32 v170, v170
	v_rcp_f32_e32 v171, v171
	v_pk_mul_f32 v[164:165], v[164:165], v[190:191] op_sel_hi:[1,0]
	v_pk_mul_f32 v[166:167], v[166:167], v[190:191] op_sel_hi:[1,0]
	v_pk_mul_f32 v[168:169], v[168:169], v[190:191] op_sel_hi:[1,0]
	v_pk_mul_f32 v[170:171], v[170:171], v[190:191] op_sel_hi:[1,0]
	v_pk_mul_f32 v[46:47], v[38:39], v[46:47]
	v_pk_mul_f32 v[48:49], v[40:41], v[48:49]
	v_pk_mul_f32 v[42:43], v[34:35], v[42:43]
	v_pk_mul_f32 v[44:45], v[36:37], v[44:45]
	v_pk_mul_f32 v[46:47], v[46:47], v[164:165]
	v_pk_mul_f32 v[48:49], v[48:49], v[166:167]
	v_pk_mul_f32 v[42:43], v[42:43], v[168:169]
	v_pk_mul_f32 v[44:45], v[44:45], v[170:171]
	v_cvt_pk_f16_f32 v176, v46, v47
	v_cvt_pk_f16_f32 v177, v48, v49
	v_cvt_pk_f16_f32 v178, v42, v43
	v_cvt_pk_f16_f32 v179, v44, v45
	global_store_dwordx4 v175, v[176:179], s[6:7]
	v_add_u32_e32 v175, s98, v175
	v_mul_f32_e32 v188, 0xbfb8aa3b, v186
	v_mul_f32_e32 v190, v186, v186
	v_pk_mul_f32 v[164:165], v[22:23], v[188:189] op_sel_hi:[1,0]
	v_pk_mul_f32 v[166:167], v[24:25], v[188:189] op_sel_hi:[1,0]
	v_pk_mul_f32 v[168:169], v[18:19], v[188:189] op_sel_hi:[1,0]
	v_pk_mul_f32 v[170:171], v[20:21], v[188:189] op_sel_hi:[1,0]
	v_exp_f32_e32 v164, v164
	v_exp_f32_e32 v165, v165
	v_exp_f32_e32 v166, v166
	v_exp_f32_e32 v167, v167
	v_exp_f32_e32 v168, v168
	v_exp_f32_e32 v169, v169
	v_exp_f32_e32 v170, v170
	v_exp_f32_e32 v171, v171
	v_pk_add_f32 v[164:165], v[164:165], v[192:193]
	v_pk_add_f32 v[166:167], v[166:167], v[192:193]
	v_pk_add_f32 v[168:169], v[168:169], v[192:193]
	v_pk_add_f32 v[170:171], v[170:171], v[192:193]
	v_rcp_f32_e32 v164, v164
	v_rcp_f32_e32 v165, v165
	v_rcp_f32_e32 v166, v166
	v_rcp_f32_e32 v167, v167
	v_rcp_f32_e32 v168, v168
	v_rcp_f32_e32 v169, v169
	v_rcp_f32_e32 v170, v170
	v_rcp_f32_e32 v171, v171
	v_pk_mul_f32 v[164:165], v[164:165], v[190:191] op_sel_hi:[1,0]
	v_pk_mul_f32 v[166:167], v[166:167], v[190:191] op_sel_hi:[1,0]
	v_pk_mul_f32 v[168:169], v[168:169], v[190:191] op_sel_hi:[1,0]
	v_pk_mul_f32 v[170:171], v[170:171], v[190:191] op_sel_hi:[1,0]
	v_pk_mul_f32 v[30:31], v[22:23], v[30:31]
	v_pk_mul_f32 v[32:33], v[24:25], v[32:33]
	v_pk_mul_f32 v[26:27], v[18:19], v[26:27]
	v_pk_mul_f32 v[28:29], v[20:21], v[28:29]
	v_pk_mul_f32 v[30:31], v[30:31], v[164:165]
	v_pk_mul_f32 v[32:33], v[32:33], v[166:167]
	v_pk_mul_f32 v[26:27], v[26:27], v[168:169]
	v_pk_mul_f32 v[28:29], v[28:29], v[170:171]
	v_cvt_pk_f16_f32 v176, v30, v31
	v_cvt_pk_f16_f32 v177, v32, v33
	v_cvt_pk_f16_f32 v178, v26, v27
	v_cvt_pk_f16_f32 v179, v28, v29
	global_store_dwordx4 v175, v[176:179], s[6:7]
	v_add_u32_e32 v175, s98, v175
	v_mul_f32_e32 v188, 0xbfb8aa3b, v187
	v_mul_f32_e32 v190, v187, v187
	v_pk_mul_f32 v[164:165], v[6:7], v[188:189] op_sel_hi:[1,0]
	v_pk_mul_f32 v[166:167], v[8:9], v[188:189] op_sel_hi:[1,0]
	v_pk_mul_f32 v[168:169], v[2:3], v[188:189] op_sel_hi:[1,0]
	v_pk_mul_f32 v[170:171], v[4:5], v[188:189] op_sel_hi:[1,0]
	v_exp_f32_e32 v164, v164
	v_exp_f32_e32 v165, v165
	v_exp_f32_e32 v166, v166
	v_exp_f32_e32 v167, v167
	v_exp_f32_e32 v168, v168
	v_exp_f32_e32 v169, v169
	v_exp_f32_e32 v170, v170
	v_exp_f32_e32 v171, v171
	v_pk_add_f32 v[164:165], v[164:165], v[192:193]
	v_pk_add_f32 v[166:167], v[166:167], v[192:193]
	v_pk_add_f32 v[168:169], v[168:169], v[192:193]
	v_pk_add_f32 v[170:171], v[170:171], v[192:193]
	v_rcp_f32_e32 v164, v164
	v_rcp_f32_e32 v165, v165
	v_rcp_f32_e32 v166, v166
	v_rcp_f32_e32 v167, v167
	v_rcp_f32_e32 v168, v168
	v_rcp_f32_e32 v169, v169
	v_rcp_f32_e32 v170, v170
	v_rcp_f32_e32 v171, v171
	v_pk_mul_f32 v[164:165], v[164:165], v[190:191] op_sel_hi:[1,0]
	v_pk_mul_f32 v[166:167], v[166:167], v[190:191] op_sel_hi:[1,0]
	v_pk_mul_f32 v[168:169], v[168:169], v[190:191] op_sel_hi:[1,0]
	v_pk_mul_f32 v[170:171], v[170:171], v[190:191] op_sel_hi:[1,0]
	v_pk_mul_f32 v[14:15], v[6:7], v[14:15]
	v_pk_mul_f32 v[16:17], v[8:9], v[16:17]
	v_pk_mul_f32 v[10:11], v[2:3], v[10:11]
	v_pk_mul_f32 v[12:13], v[4:5], v[12:13]
	v_pk_mul_f32 v[14:15], v[14:15], v[164:165]
	v_pk_mul_f32 v[16:17], v[16:17], v[166:167]
	v_pk_mul_f32 v[10:11], v[10:11], v[168:169]
	v_pk_mul_f32 v[12:13], v[12:13], v[170:171]
	v_cvt_pk_f16_f32 v176, v14, v15
	v_cvt_pk_f16_f32 v177, v16, v17
	v_cvt_pk_f16_f32 v178, v10, v11
	v_cvt_pk_f16_f32 v179, v12, v13
	global_store_dwordx4 v175, v[176:179], s[6:7]
	s_cbranch_vccnz .LBB0_1010
	s_andn2_b64 vcc, exec, s[4:5]
	s_cbranch_vccnz .LBB0_1009
	s_barrier
	s_branch .LBB0_1009
